# combo14 + E46: in PD three of the four CUs of an XCD that share a (head, 4-chunk group)'s K/V blocks start ~2 us after the first (s_sleep 60) so they hit the L2 instead of merging into the same misses
# speedup vs baseline: 1.0229x; 1.0014x over previous
.LBB0_137:
	v_readlane_b32 s0, v251, 47
	v_readlane_b32 s1, v251, 48
	s_andn2_b64 vcc, exec, s[0:1]
	v_readlane_b32 s14, v253, 60
	s_mov_b32 s15, s57
	s_mov_b32 s16, s57
	s_cbranch_vccnz .Lpd_nosleep
	s_bfe_u32 s2, s57, 0x20003
	s_cmp_eq_u32 s2, 0
	s_cbranch_scc1 .Lpd_nosleep
	s_sleep 60
.Lpd_nosleep:
	s_cbranch_vccz .LBB0_199
